# v15 plus attention K-tile LDS XOR swizzle keyed on row bits 3:1 instead of 2:0 (conflict-free for 16-lane ds_read_b128 groups at 384-byte pitch)
# speedup vs baseline: 1.0198x; 1.0069x over previous
; __device__ __forceinline__ int v_st(int k, int c) { const int kk = (k & ~0xC) | ((k & 4) << 1) | ((k & 8) >> 1); return ((kk >> 3) * 4 + (c >> 5)) * 512 + ((kk & 7) * 32 + (c & 31)) * 2; }
; __device__ __forceinline__ int v_rd_base(int lane) { return ((lane & 3) << 3) | (((lane >> 2) & 3) << 6) | (((lane >> 4) & 1) << 5) | (((lane >> 5) & 1) << 8); }
; #define VMW() asm volatile("s_waitcnt vmcnt(0)" ::: "memory")
; __device__ __forceinline__ void attn_prime(const BlockRef& cur, char* lds, Seam& S) {
;     const int tid = threadIdx.x, wid = __builtin_amdgcn_readfirstlane(tid >> 6), lane = tid & 63, r32 = lane & 31, hi = lane >> 5;
;     const int sr = tid >> 4, sc = (tid & 15) * 8, rr = tid >> 3, rc = (tid & 7) * 8, kws = KSWZ(sr, sc * 2), kws2 = KSWZ(rr, (128 + rc) * 2); char* K_lds = lds;
;     const unsigned voff = (unsigned)(sr * 2048 + sc), roff = (unsigned)(rr * 64 + rc), qoff = (unsigned)((wid * QBLK + r32) * 2048 + hi * 8);
;     QLOAD(cur);
;     SLOAD_H(cur, 0); VMW(); SWRITE_HK(0);
;     __syncthreads();
; }
; __device__ __forceinline__ void attn_block(const BlockRef& cur, const BlockRef& nxt, char* lds, Seam& S) {
;     const int tid = threadIdx.x, wid = __builtin_amdgcn_readfirstlane(tid >> 6), lane = tid & 63, r32 = lane & 31, hi = lane >> 5;
;     const int NT = (cur.P0 + QB) / KVBLK;
;     const int qlo = cur.P0 + wid * QBLK, qm = qlo + r32 - 4 * hi;
;     char* K_lds = lds; char* V_lds = lds + 2 * SHM_K;
;     float* ws = (float*)(lds + 2 * SHM_V + 2 * SHM_K) + wid * 64; float* li_l = ws, * al_l = ws + 32;
;     char* qx = lds + LDS_QX + wid * 4096 + lane * 16;
;     { bf16x8 t4[4];
; #pragma unroll
;       for (int d0 = 0; d0 < 4; ++d0) t4[d0] = *(const bf16x8*)(cur.QR + d0 * 16 + (unsigned)((wid * QBLK + r32) * 1024 + hi * 8));
; #pragma unroll
;       for (int d0 = 0; d0 < 4; ++d0) *(bf16x8*)(qx + d0 * 1024) = t4[d0]; }
;     float m_reg = -1e30f, l_reg = 0; f32x16 o[4] = {};
;     const int sr = tid >> 4, sc = (tid & 15) * 8, rr = tid >> 3, rc = (tid & 7) * 8;
;     const unsigned voff = (unsigned)(sr * 2048 + sc), roff = (unsigned)(rr * 64 + rc), qoff = (unsigned)((wid * QBLK + r32) * 2048 + hi * 8);
;     const int vst0 = v_st(sr, sc), vst1 = v_st(32 + sr, sc), kws = KSWZ(sr, sc * 2), kws2 = KSWZ(rr, (128 + rc) * 2);
;     const int vb0 = (int)(uintptr_t)V_lds + v_rd_base(lane);
.LBB0_956:
	s_add_u32 s7, s90, 0x1a800000
	s_addc_u32 s8, s91, 0
	v_writelane_b32 v254, s86, 23
	s_add_u32 s11, s90, 0x22800000
	s_mov_b64 s[0:1], s[88:89]
	v_writelane_b32 v254, s87, 24
	s_addc_u32 s12, s91, 0
	s_mov_b64 s[2:3], s[90:91]
	s_mov_b64 s[4:5], s[92:93]
	s_add_u32 s13, s90, 0x26800000
	v_writelane_b32 v254, s0, 25
	s_addc_u32 s14, s91, 0
	s_add_u32 s15, s90, 0x12000000
	v_writelane_b32 v254, s1, 26
	v_writelane_b32 v254, s2, 27
	s_addc_u32 s16, s91, 0
	v_writelane_b32 v254, s3, 28
	s_add_u32 s17, s90, 0x2e800000
	v_writelane_b32 v254, s4, 29
	s_addc_u32 s18, s91, 0
	v_writelane_b32 v254, s5, 30
	s_add_u32 s19, s90, 0x12800000
	v_writelane_b32 v254, s6, 31
	v_writelane_b32 v254, s7, 32
	s_addc_u32 s20, s91, 0
	s_ashr_i32 s0, s69, 31
	s_lshr_b32 s0, s0, 28
	s_add_i32 s0, s69, s0
	s_and_b32 s1, s0, -16
	s_sub_i32 s22, s69, s1
	s_ashr_i32 s4, s0, 8
	s_ashr_i32 s2, s0, 4
	s_ashr_i32 s5, s4, 31
	s_ashr_i32 s23, s22, 31
	v_writelane_b32 v254, s2, 33
	s_and_b32 s6, s2, 15
	s_lshl_b64 s[0:1], s[22:23], 19
	s_lshl_b64 s[2:3], s[4:5], 24
	s_add_u32 s0, s2, s0
	s_addc_u32 s1, s3, s1
	s_lshl_b64 s[2:3], s[0:1], 1
	v_writelane_b32 v254, s7, 34
	s_add_u32 s7, s7, s2
	v_writelane_b32 v254, s8, 35
	s_addc_u32 s8, s8, s3
	s_lshl_b32 s9, s6, 7
	s_lshl_b32 s10, s6, 8
	s_add_u32 s86, s7, s10
	s_addc_u32 s87, s8, 0
	s_add_u32 s0, s11, s0
	s_addc_u32 s1, s12, s1
	s_add_u32 s0, s0, s9
	s_addc_u32 s1, s1, 0
	s_lshl_b64 s[6:7], s[4:5], 25
	s_add_u32 s8, s13, s6
	s_addc_u32 s9, s14, s7
	s_add_u32 s96, s8, s10
	s_addc_u32 s97, s9, 0
	s_lshl_b64 s[4:5], s[4:5], 20
	s_waitcnt vmcnt(0)
	v_lshlrev_b32_e32 v4, 3, v168
	s_add_u32 s36, s15, s4
	v_lshrrev_b32_e32 v6, 4, v168
	v_and_b32_e32 v7, 0x78, v4
	s_addc_u32 s37, s16, s5
	v_mov_b32_e32 v165, 0
	v_lshl_or_b32 v166, v6, 11, v7
	v_lshlrev_b32_e32 v170, 1, v166
	v_mov_b32_e32 v171, v165
	s_add_u32 s4, s17, s6
	s_mov_b32 s8, 0x20000
	v_lshl_add_u64 v[2:3], s[96:97], 0, v[170:171]
	s_addc_u32 s5, s18, s7
	v_add_co_u32_e32 v2, vcc, s8, v2
	s_add_u32 s70, s4, s10
	v_writelane_b32 v254, s11, 36
	v_addc_co_u32_e32 v3, vcc, 0, v3, vcc
	s_addc_u32 s71, s5, 0
	v_writelane_b32 v254, s12, 37
	global_load_dwordx4 v[128:131], v170, s[96:97]
	global_load_dwordx4 v[136:139], v[2:3], off
	v_lshl_add_u64 v[2:3], s[70:71], 0, v[170:171]
	v_writelane_b32 v254, s13, 38
	v_add_co_u32_e32 v2, vcc, s8, v2
	v_writelane_b32 v254, s14, 39
	v_lshrrev_b32_e32 v1, 3, v168
	s_waitcnt lgkmcnt(0)
	v_and_b32_e32 v5, 56, v4
	v_addc_co_u32_e32 v3, vcc, 0, v3, vcc
	v_lshlrev_b32_e32 v9, 1, v168
	v_writelane_b32 v254, s15, 40
	v_lshl_or_b32 v0, v1, 6, v5
	global_load_dwordx4 v[132:135], v[2:3], off
	s_movk_i32 s5, 0x70
	s_movk_i32 s6, 0x100
	v_and_b32_e32 v3, 0x70, v168
	v_lshlrev_b32_e32 v5, 1, v5
	v_lshlrev_b32_e32 v7, 1, v7
	v_writelane_b32 v254, s16, 41
	v_bitop3_b32 v5, v5, v3, s6 bitop3:0x36
	v_lshrrev_b32_e32 v3, 1, v168
	v_bitop3_b32 v3, v7, v3, s5 bitop3:0x78
	s_add_u32 s5, s19, s2
	v_writelane_b32 v254, s17, 42
	s_addc_u32 s6, s20, s3
	v_writelane_b32 v254, s18, 43
	s_add_u32 s82, s5, s10
	v_writelane_b32 v254, s19, 44
	s_addc_u32 s83, s6, 0
	v_writelane_b32 v254, s20, 45
	s_add_u32 s2, s94, s2
	v_writelane_b32 v254, s94, 46
	s_addc_u32 s3, s95, s3
	v_readfirstlane_b32 s4, v168
	s_add_u32 s88, s2, s10
	s_movk_i32 s7, 0x180
	s_addc_u32 s89, s3, 0
	s_lshr_b32 s2, s4, 1
	v_and_b32_e32 v167, 31, v168
	v_lshrrev_b32_e32 v2, 2, v168
	v_mad_u32_u24 v10, v6, s7, 0
	s_and_b32 s2, s2, 0x1fffe0
	v_and_b32_e32 v2, 8, v2
	v_add_u32_e32 v169, v10, v3
	v_or_b32_e32 v3, s2, v167
	v_lshl_or_b32 v164, v3, 11, v2
	v_lshlrev_b32_e32 v8, 1, v0
	v_lshl_add_u64 v[2:3], v[164:165], 1, s[86:87]
	global_load_dwordx4 v[140:143], v8, s[36:37]
	global_load_dwordx4 v[144:147], v170, s[70:71]
	global_load_dwordx4 v[124:127], v[2:3], off
	global_load_dwordx4 v[120:123], v[2:3], off offset:32
	global_load_dwordx4 v[116:119], v[2:3], off offset:64
	global_load_dwordx4 v[112:115], v[2:3], off offset:96
	global_load_dwordx4 v[108:111], v[2:3], off offset:128
	global_load_dwordx4 v[104:107], v[2:3], off offset:160
	global_load_dwordx4 v[100:103], v[2:3], off offset:192
	global_load_dwordx4 v[96:99], v[2:3], off offset:224
	v_mad_u32_u24 v11, v1, s7, 0
	v_add_u32_e32 v182, v11, v5
	v_and_b32_e32 v11, 48, v6
	v_and_or_b32 v1, v1, 8, v11
	v_lshrrev_b32_e32 v11, 5, v168
	v_lshrrev_b32_e32 v1, 1, v1
	v_bfe_u32 v12, v4, 5, 2
	v_bfe_u32 v13, v168, 4, 2
	v_or_b32_e32 v1, v1, v12
	v_and_or_b32 v11, v11, 4, v13
	v_lshlrev_b32_e32 v1, 9, v1
	v_lshlrev_b32_e32 v11, 6, v11
	v_and_b32_e32 v7, 48, v7
	v_or3_b32 v186, v1, v11, v7
	v_add_u32_e32 v1, 32, v6
	v_and_b32_e32 v6, 0x70, v1
	v_lshlrev_b32_e32 v1, 1, v1
	v_and_or_b32 v1, v1, 8, v6
	v_writelane_b32 v254, s95, 47
	s_mov_b32 s2, s22
	v_lshrrev_b32_e32 v1, 1, v1
	v_writelane_b32 v254, s2, 48
	v_and_b32_e32 v2, 63, v168
	v_or_b32_e32 v1, v1, v12
	v_writelane_b32 v254, s3, 49
	v_lshlrev_b32_e32 v5, 4, v2
	s_add_i32 s2, 0, 0x14800
	v_lshlrev_b32_e32 v1, 9, v1
	v_add_u32_e32 v185, s2, v5
	v_or3_b32 v187, v1, v11, v7
	v_and_b32_e32 v1, 0xc0, v5
	v_and_b32_e32 v5, 32, v9
	v_and_b32_e32 v4, 0x118, v4
	s_lshl_b32 s68, s22, 8
	v_bfe_u32 v3, v168, 5, 1
	v_or3_b32 v1, v4, v5, v1
	s_add_i32 s2, 0, 0xc000
	v_lshlrev_b32_e32 v4, 3, v168
	v_lshlrev_b32_e32 v183, 2, v3
	v_lshlrev_b32_e32 v10, 3, v3
	s_cmp_lg_u32 s2, -1
	v_lshlrev_b32_e32 v3, 4, v3
	v_and_b32_e32 v4, 0x70, v4
	s_waitcnt vmcnt(0)
	s_cselect_b32 s2, s2, 0
	v_xad_u32 v5, v3, v4, 0
	v_or_b32_e32 v6, 32, v3
	v_or_b32_e32 v7, 64, v3
	v_or_b32_e32 v3, 0x60, v3
	v_sub_u32_e32 v184, v167, v183
	v_add_u32_e32 v188, s2, v1
	v_mul_u32_u24_e32 v1, 0x180, v167
	v_xad_u32 v6, v6, v4, 0
	v_xad_u32 v7, v7, v4, 0
	v_xad_u32 v3, v3, v4, 0
	v_cmp_gt_u32_e64 s[2:3], 32, v2
	v_and_b32_e32 v2, 1, v168
	v_lshlrev_b32_e32 v174, 1, v0
	v_mbcnt_lo_u32_b32 v0, -1, 0
	s_mov_b32 s11, 0
	v_and_b32_e32 v189, 60, v9
	v_cmp_eq_u32_e64 s[4:5], 0, v2
	v_or_b32_e32 v190, v2, v183
	v_add_u32_e32 v191, 0xffffff80, v184
	v_or_b32_e32 v172, 0x4000, v8
	v_mov_b32_e32 v173, v165
	s_mov_b32 s33, 0x41000000
	s_mov_b32 s90, 0x3dd53b94
	s_add_i32 s6, 0, 0x10000
	s_mov_b32 s76, 0x80000
	s_mov_b32 s77, 0xa0000
	v_mbcnt_hi_u32_b32 v192, -1, v0
	v_lshlrev_b32_e32 v193, 1, v10
	v_add_u32_e32 v194, v5, v1
	v_add_u32_e32 v195, v6, v1
	v_add_u32_e32 v196, v7, v1
	v_add_u32_e32 v197, v3, v1
	v_mov_b32_e32 v198, 0xff800000
	v_mov_b32_e32 v199, 0xf149f2ca
	s_waitcnt vmcnt(12)
	ds_write_b128 v169, v[128:131]
	s_waitcnt vmcnt(11)
	ds_write_b128 v169, v[136:139] offset:12288
	s_waitcnt vmcnt(9)
	ds_write_b128 v182, v[140:143]
	s_waitcnt lgkmcnt(0)
	s_barrier
	v_writelane_b32 v254, s6, 50
	s_branch .LBB0_958
